# XCD-local barriers at GEMM-to-GEMM seams with run-time placement check and full-barrier fallback
# speedup vs baseline: 1.0396x; 1.0181x over previous
; #define LAS __attribute__((address_space(3)))
; __device__ __forceinline__ unsigned xb_add(unsigned* p, unsigned v) { return __hip_atomic_fetch_add(p, v, __ATOMIC_RELAXED, __HIP_MEMORY_SCOPE_AGENT); }
; __device__ __forceinline__ unsigned xb_xcc_id() { return (unsigned)__builtin_amdgcn_s_getreg((3 << 11) | 20) & 0xFu; }
; __device__ __forceinline__ XcdBarrier xcd_barrier_post(unsigned* bar, volatile LAS unsigned* st) {
;     XcdBarrier b; b.bar = bar; b.x = xb_xcc_id(); b.st = st;
;     if (threadIdx.x == 0) (void)xb_add(&bar[XB_XCNT(b.x)], 1u);
;     return b;
; __global__ void __launch_bounds__(512, 2) fwd_megakernel(Args args) {
;     ...
;     volatile LAS unsigned* bst = (volatile LAS unsigned*)(lds + 147440);
;     if (threadIdx.x < 4) bst[threadIdx.x] = 0u;
;     __syncthreads();
;     (void)xcd_barrier_post((unsigned*)(args.ws + WS_BAR), bst);
.LBB0_14:
	s_load_dwordx16 s[4:19], s[0:1], 0x0
	v_cmp_gt_u32_e32 vcc, 4, v195
	s_waitcnt lgkmcnt(0)
	v_writelane_b32 v251, s4, 9
	s_nop 1
	v_writelane_b32 v251, s5, 10
	v_writelane_b32 v251, s6, 11
	v_writelane_b32 v251, s7, 12
	v_writelane_b32 v251, s8, 13
	v_writelane_b32 v251, s9, 14
	v_writelane_b32 v251, s10, 15
	v_writelane_b32 v251, s11, 16
	v_writelane_b32 v251, s12, 17
	v_writelane_b32 v251, s13, 18
	v_writelane_b32 v251, s14, 19
	v_writelane_b32 v251, s15, 20
	v_writelane_b32 v251, s16, 21
	v_writelane_b32 v251, s17, 22
	v_writelane_b32 v251, s18, 23
	v_writelane_b32 v251, s19, 24
	s_load_dwordx16 s[4:19], s[0:1], 0x40
	s_waitcnt lgkmcnt(0)
	v_writelane_b32 v251, s4, 25
	s_nop 1
	v_writelane_b32 v251, s5, 26
	v_writelane_b32 v251, s6, 27
	v_writelane_b32 v251, s7, 28
	v_writelane_b32 v251, s8, 29
	v_writelane_b32 v251, s9, 30
	v_writelane_b32 v251, s10, 31
	v_writelane_b32 v251, s11, 32
	v_writelane_b32 v251, s12, 33
	v_writelane_b32 v251, s13, 34
	v_writelane_b32 v251, s14, 35
	v_writelane_b32 v251, s15, 36
	v_writelane_b32 v251, s16, 37
	v_writelane_b32 v251, s17, 38
	v_writelane_b32 v251, s18, 39
	v_writelane_b32 v251, s19, 40
	s_load_dwordx16 s[4:19], s[0:1], 0x80
	s_waitcnt lgkmcnt(0)
	v_writelane_b32 v251, s4, 41
	s_nop 1
	v_writelane_b32 v251, s5, 42
	v_writelane_b32 v251, s6, 43
	v_writelane_b32 v251, s7, 44
	v_writelane_b32 v251, s8, 45
	v_writelane_b32 v251, s9, 46
	v_writelane_b32 v251, s10, 47
	v_writelane_b32 v251, s11, 48
	v_writelane_b32 v251, s12, 49
	v_writelane_b32 v251, s13, 50
	v_writelane_b32 v251, s14, 51
	v_writelane_b32 v251, s15, 52
	v_writelane_b32 v251, s16, 53
	v_writelane_b32 v251, s17, 54
	v_writelane_b32 v251, s18, 55
	v_writelane_b32 v251, s19, 56
	s_and_saveexec_b64 s[0:1], vcc
	v_lshl_add_u32 v0, v195, 2, 0
	v_add_u32_e32 v0, 0x23ff0, v0
	v_mov_b32_e32 v1, 0
	ds_write_b32 v0, v1
	s_or_b64 exec, exec, s[0:1]
	s_add_u32 s8, s80, 0x10000
	s_waitcnt lgkmcnt(0)
	s_barrier
	s_addc_u32 s9, s81, 0
	s_getreg_b32 s0, hwreg(HW_REG_XCC_ID, 0, 4)
	s_mov_b32 s1, 0
	v_cmp_eq_u32_e64 s[4:5], 0, v195
	s_mov_b64 s[2:3], exec
	s_nop 0
	v_writelane_b32 v251, s4, 57
	s_nop 1
	v_writelane_b32 v251, s5, 58
	s_and_b64 s[4:5], s[2:3], s[4:5]
	s_mov_b64 exec, s[4:5]
	s_cbranch_execz .LBB0_19
	s_mov_b64 s[4:5], exec
	v_mbcnt_lo_u32_b32 v0, s4, 0
	v_mbcnt_hi_u32_b32 v0, s5, v0
	v_cmp_eq_u32_e32 vcc, 0, v0
	s_and_b64 s[6:7], exec, vcc
	s_mov_b64 exec, s[6:7]
	s_cbranch_execz .LBB0_19
	s_lshl_b32 s0, s0, 8
	s_and_b32 s0, s0, 0xf00
	s_bcnt1_i32_b64 s4, s[4:5]
	v_mov_b32_e32 v0, s0
	v_mov_b32_e32 v1, s4
	global_atomic_add v0, v1, s[8:9] offset:1024
	s_lshr_b32 s4, s0, 8
	s_lshl_b32 s4, 1, s4
	v_mov_b32_e32 v1, s4
	v_readlane_b32 s4, v251, 0
	s_and_b32 s4, s4, 7
	s_lshl_b32 s4, s4, 2
	v_mov_b32_e32 v0, s4
	s_nop 0
	global_atomic_or v0, v1, s[8:9]

; __device__ __forceinline__ unsigned xb_ld(unsigned* p)              { return __hip_atomic_load(p, __ATOMIC_RELAXED, __HIP_MEMORY_SCOPE_AGENT); }
; __device__ __forceinline__ unsigned xb_add(unsigned* p, unsigned v) { return __hip_atomic_fetch_add(p, v, __ATOMIC_RELAXED, __HIP_MEMORY_SCOPE_AGENT); }
; #define XB_SPIN(cond, bar) do { unsigned _sp = 0; while (cond) { __builtin_amdgcn_s_sleep(1); \
;     if ((++_sp & 255u) == 0u) { if (xb_ld(&(bar)[XB_TMO])) break; if (_sp > XB_SPIN_CAP) { atomicAdd(&(bar)[XB_TMO], 1u); break; } } } } while (0)
; __device__ __forceinline__ void xcd_barrier(const XcdBarrier& b) {
;     asm volatile("s_waitcnt vmcnt(0)" ::: "memory");
;     __syncthreads();
;     if (threadIdx.x == 0) {
;         unsigned* bar = b.bar;
;         __builtin_amdgcn_s_waitcnt(0);
;         unsigned nloc = b.st[0], nx = b.st[1];
;         if (nloc == 0u) { xcd_barrier_complete(bar, b.x, nloc, nx); b.st[0] = nloc; b.st[1] = nx; }
;         const unsigned old = xb_add(&bar[XB_XSUB(b.x)], 1u);
;         const unsigned gen = old / nloc;
;         if (old + 1u == (gen + 1u) * nloc) {
;             __builtin_amdgcn_fence(__ATOMIC_RELEASE, "agent");
;             asm volatile("s_waitcnt vmcnt(0)" ::: "memory");
;             const unsigned og = xb_add(&bar[XB_TOP], 1u);
;             const unsigned tg = og / nx;
;             if (og + 1u == (tg + 1u) * nx) xb_add(&bar[XB_TOPGEN], 1u);
;             else XB_SPIN(xb_ld(&bar[XB_TOPGEN]) == tg, bar);
;             __builtin_amdgcn_fence(__ATOMIC_ACQUIRE, "agent");
;             xb_add(&bar[XB_XGEN(b.x)], 1u);
;             asm volatile("s_waitcnt vmcnt(0)" ::: "memory");
;         } else {
;             XB_SPIN(xb_ld(&bar[XB_XGEN(b.x)]) == gen, bar);
;             __builtin_amdgcn_fence(__ATOMIC_ACQUIRE, "agent");
;             asm volatile("s_waitcnt vmcnt(0)" ::: "memory");
;         }
.LBB0_172:
	s_getreg_b32 s2, hwreg(HW_REG_XCC_ID, 0, 4)
	s_waitcnt vmcnt(0)
	s_waitcnt vmcnt(0) lgkmcnt(0)
	s_barrier
	s_and_saveexec_b64 s[4:5], s[76:77]
	s_xor_b64 s[4:5], exec, s[4:5]
	s_cbranch_execz .LBB0_225
	v_mov_b32_e32 v0, 0x23ff8
	ds_read_b32 v2, v0
	s_waitcnt lgkmcnt(0)
	v_readfirstlane_b32 s3, v2
	s_cmp_eq_u32 s3, 1
	s_cbranch_scc1 .Lfb2_fast
	s_cmp_eq_u32 s3, 2
	s_cbranch_scc1 .Lfb2_slow
	s_add_u32 s8, s80, 0x10000
	s_addc_u32 s9, s81, 0
	v_mov_b32_e32 v1, 0
	global_load_dwordx4 v[4:7], v1, s[8:9] sc1
	global_load_dwordx4 v[8:11], v1, s[8:9] offset:16 sc1
	s_mov_b32 s6, 1
	s_waitcnt vmcnt(0)
	v_readfirstlane_b32 s3, v4
	s_sub_u32 s7, s3, 1
	s_and_b32 s7, s7, s3
	s_cmp_lg_u32 s7, 0
	s_cselect_b32 s6, 2, s6
	s_cmp_eq_u32 s3, 0
	s_cselect_b32 s6, 2, s6
	v_readfirstlane_b32 s3, v5
	s_sub_u32 s7, s3, 1
	s_and_b32 s7, s7, s3
	s_cmp_lg_u32 s7, 0
	s_cselect_b32 s6, 2, s6
	s_cmp_eq_u32 s3, 0
	s_cselect_b32 s6, 2, s6
	v_readfirstlane_b32 s3, v6
	s_sub_u32 s7, s3, 1
	s_and_b32 s7, s7, s3
	s_cmp_lg_u32 s7, 0
	s_cselect_b32 s6, 2, s6
	s_cmp_eq_u32 s3, 0
	s_cselect_b32 s6, 2, s6
	v_readfirstlane_b32 s3, v7
	s_sub_u32 s7, s3, 1
	s_and_b32 s7, s7, s3
	s_cmp_lg_u32 s7, 0
	s_cselect_b32 s6, 2, s6
	s_cmp_eq_u32 s3, 0
	s_cselect_b32 s6, 2, s6
	v_readfirstlane_b32 s3, v8
	s_sub_u32 s7, s3, 1
	s_and_b32 s7, s7, s3
	s_cmp_lg_u32 s7, 0
	s_cselect_b32 s6, 2, s6
	s_cmp_eq_u32 s3, 0
	s_cselect_b32 s6, 2, s6
	v_readfirstlane_b32 s3, v9
	s_sub_u32 s7, s3, 1
	s_and_b32 s7, s7, s3
	s_cmp_lg_u32 s7, 0
	s_cselect_b32 s6, 2, s6
	s_cmp_eq_u32 s3, 0
	s_cselect_b32 s6, 2, s6
	v_readfirstlane_b32 s3, v10
	s_sub_u32 s7, s3, 1
	s_and_b32 s7, s7, s3
	s_cmp_lg_u32 s7, 0
	s_cselect_b32 s6, 2, s6
	s_cmp_eq_u32 s3, 0
	s_cselect_b32 s6, 2, s6
	v_readfirstlane_b32 s3, v11
	s_sub_u32 s7, s3, 1
	s_and_b32 s7, s7, s3
	s_cmp_lg_u32 s7, 0
	s_cselect_b32 s6, 2, s6
	s_cmp_eq_u32 s3, 0
	s_cselect_b32 s6, 2, s6
	s_cmpk_lg_u32 s82, 0x100
	s_cselect_b32 s6, 2, s6
	v_mov_b32_e32 v0, 0x23ff8
	v_mov_b32_e32 v2, s6
	ds_write_b32 v0, v2
	s_waitcnt lgkmcnt(0)
	s_cmp_eq_u32 s6, 1
	s_cbranch_scc1 .Lfb2_fast
	s_branch .Lfb2_slow
.Lfb2_fast:
	v_readlane_b32 s3, v251, 0
	s_and_b32 s6, s3, 7
	s_lshl_b32 s6, s6, 5
	s_add_u32 s8, s80, 0x10040
	s_addc_u32 s9, s81, 0
	s_add_u32 s8, s8, s6
	s_addc_u32 s9, s9, 0
	v_mov_b32_e32 v0, 0
	v_mov_b32_e32 v1, 1
	global_atomic_add v2, v0, v1, s[8:9] sc0
	s_waitcnt vmcnt(0)
	v_readfirstlane_b32 s3, v2
	s_lshr_b32 s7, s3, 5
	s_add_i32 s7, s7, 1
	s_and_b32 s3, s3, 31
	s_cmp_eq_u32 s3, 31
	s_cbranch_scc0 .Lfb2_spin0
	global_atomic_add v0, v1, s[8:9] offset:4
	s_branch .Lfb2_rel
.Lfb2_spin0:
	s_mov_b32 s16, 0
.Lfb2_spin:
	s_sleep 1
	global_load_dword v2, v0, s[8:9] offset:4 sc1
	s_add_i32 s16, s16, 1
	s_waitcnt vmcnt(0)
	v_readfirstlane_b32 s3, v2
	s_cmp_ge_u32 s3, s7
	s_cbranch_scc1 .Lfb2_rel
	s_cmp_lt_u32 s16, 0x8000
	s_cbranch_scc1 .Lfb2_spin
.Lfb2_rel:
	buffer_inv sc1
	s_waitcnt vmcnt(0)
	s_branch .LBB0_225

; __device__ __forceinline__ void xcd_barrier(const XcdBarrier& b) {
;     asm volatile("s_waitcnt vmcnt(0)" ::: "memory");
;     __syncthreads();
;     if (threadIdx.x == 0) {
;         unsigned* bar = b.bar;
;         __builtin_amdgcn_s_waitcnt(0);
;         unsigned nloc = b.st[0], nx = b.st[1];
;         if (nloc == 0u) { xcd_barrier_complete(bar, b.x, nloc, nx); b.st[0] = nloc; b.st[1] = nx; }
.LBB0_267:
	s_getreg_b32 s2, hwreg(HW_REG_XCC_ID, 0, 4)
	s_waitcnt vmcnt(0)
	s_waitcnt lgkmcnt(0)
	s_barrier
	s_and_saveexec_b64 s[4:5], s[76:77]
	s_cbranch_execz .LBB0_319
	v_mov_b32_e32 v0, 0x23ff8
	ds_read_b32 v2, v0
	s_waitcnt lgkmcnt(0)
	v_readfirstlane_b32 s3, v2
	s_cmp_eq_u32 s3, 1
	s_cbranch_scc1 .Lfb3_fast
	s_branch .Lfb3_slow

; __device__ __forceinline__ unsigned xb_ld(unsigned* p)              { return __hip_atomic_load(p, __ATOMIC_RELAXED, __HIP_MEMORY_SCOPE_AGENT); }
; __device__ __forceinline__ unsigned xb_add(unsigned* p, unsigned v) { return __hip_atomic_fetch_add(p, v, __ATOMIC_RELAXED, __HIP_MEMORY_SCOPE_AGENT); }
; #define XB_SPIN(cond, bar) do { unsigned _sp = 0; while (cond) { __builtin_amdgcn_s_sleep(1); \
;     if ((++_sp & 255u) == 0u) { if (xb_ld(&(bar)[XB_TMO])) break; if (_sp > XB_SPIN_CAP) { atomicAdd(&(bar)[XB_TMO], 1u); break; } } } } while (0)
; __device__ __forceinline__ void xcd_barrier(const XcdBarrier& b) {
;     asm volatile("s_waitcnt vmcnt(0)" ::: "memory");
;     __syncthreads();
;     if (threadIdx.x == 0) {
;         unsigned* bar = b.bar;
;         __builtin_amdgcn_s_waitcnt(0);
;         unsigned nloc = b.st[0], nx = b.st[1];
;         if (nloc == 0u) { xcd_barrier_complete(bar, b.x, nloc, nx); b.st[0] = nloc; b.st[1] = nx; }
;         const unsigned old = xb_add(&bar[XB_XSUB(b.x)], 1u);
;         const unsigned gen = old / nloc;
;         if (old + 1u == (gen + 1u) * nloc) {
;             __builtin_amdgcn_fence(__ATOMIC_RELEASE, "agent");
;             asm volatile("s_waitcnt vmcnt(0)" ::: "memory");
;             const unsigned og = xb_add(&bar[XB_TOP], 1u);
;             const unsigned tg = og / nx;
;             if (og + 1u == (tg + 1u) * nx) xb_add(&bar[XB_TOPGEN], 1u);
;             else XB_SPIN(xb_ld(&bar[XB_TOPGEN]) == tg, bar);
;             __builtin_amdgcn_fence(__ATOMIC_ACQUIRE, "agent");
;             xb_add(&bar[XB_XGEN(b.x)], 1u);
;             asm volatile("s_waitcnt vmcnt(0)" ::: "memory");
;         } else {
;             XB_SPIN(xb_ld(&bar[XB_XGEN(b.x)]) == gen, bar);
;             __builtin_amdgcn_fence(__ATOMIC_ACQUIRE, "agent");
;             asm volatile("s_waitcnt vmcnt(0)" ::: "memory");
;         }
.LBB0_1234:
	s_getreg_b32 s2, hwreg(HW_REG_XCC_ID, 0, 4)
	s_waitcnt vmcnt(0)
	s_waitcnt lgkmcnt(0)
	s_barrier
	s_and_saveexec_b64 s[4:5], s[76:77]
	s_cbranch_execz .Lfb9_skip
	v_mov_b32_e32 v0, 0x23ff8
	ds_read_b32 v2, v0
	s_waitcnt lgkmcnt(0)
	v_readfirstlane_b32 s3, v2
	s_cmp_eq_u32 s3, 1
	s_cbranch_scc0 .LBB0_1235
	v_readlane_b32 s3, v251, 0
	s_and_b32 s6, s3, 7
	s_lshl_b32 s6, s6, 5
	s_add_u32 s8, s80, 0x10040
	s_addc_u32 s9, s81, 0
	s_add_u32 s8, s8, s6
	s_addc_u32 s9, s9, 0
	v_mov_b32_e32 v0, 0
	v_mov_b32_e32 v1, 1
	global_atomic_add v2, v0, v1, s[8:9] sc0
	s_waitcnt vmcnt(0)
	v_readfirstlane_b32 s3, v2
	s_lshr_b32 s7, s3, 5
	s_add_i32 s7, s7, 1
	s_and_b32 s3, s3, 31
	s_cmp_eq_u32 s3, 31
	s_cbranch_scc0 .Lfb9_spin0
	global_atomic_add v0, v1, s[8:9] offset:4
	s_branch .Lfb9_rel

; __device__ __forceinline__ void xcd_barrier(const XcdBarrier& b) {
;     ...
;     }
;     __syncthreads();
.Lfb9_skip:
	s_getpc_b64 s[98:99]

; __device__ __forceinline__ unsigned xb_ld(unsigned* p)              { return __hip_atomic_load(p, __ATOMIC_RELAXED, __HIP_MEMORY_SCOPE_AGENT); }
; __device__ __forceinline__ unsigned xb_add(unsigned* p, unsigned v) { return __hip_atomic_fetch_add(p, v, __ATOMIC_RELAXED, __HIP_MEMORY_SCOPE_AGENT); }
; #define XB_SPIN(cond, bar) do { unsigned _sp = 0; while (cond) { __builtin_amdgcn_s_sleep(1); \
;     if ((++_sp & 255u) == 0u) { if (xb_ld(&(bar)[XB_TMO])) break; if (_sp > XB_SPIN_CAP) { atomicAdd(&(bar)[XB_TMO], 1u); break; } } } } while (0)
; __device__ __forceinline__ void xcd_barrier(const XcdBarrier& b) {
;     asm volatile("s_waitcnt vmcnt(0)" ::: "memory");
;     __syncthreads();
;     if (threadIdx.x == 0) {
;         unsigned* bar = b.bar;
;         __builtin_amdgcn_s_waitcnt(0);
;         unsigned nloc = b.st[0], nx = b.st[1];
;         if (nloc == 0u) { xcd_barrier_complete(bar, b.x, nloc, nx); b.st[0] = nloc; b.st[1] = nx; }
;         const unsigned old = xb_add(&bar[XB_XSUB(b.x)], 1u);
;         const unsigned gen = old / nloc;
;         if (old + 1u == (gen + 1u) * nloc) {
;             __builtin_amdgcn_fence(__ATOMIC_RELEASE, "agent");
;             asm volatile("s_waitcnt vmcnt(0)" ::: "memory");
;             const unsigned og = xb_add(&bar[XB_TOP], 1u);
;             const unsigned tg = og / nx;
;             if (og + 1u == (tg + 1u) * nx) xb_add(&bar[XB_TOPGEN], 1u);
;             else XB_SPIN(xb_ld(&bar[XB_TOPGEN]) == tg, bar);
;             __builtin_amdgcn_fence(__ATOMIC_ACQUIRE, "agent");
;             xb_add(&bar[XB_XGEN(b.x)], 1u);
;             asm volatile("s_waitcnt vmcnt(0)" ::: "memory");
;         } else {
;             XB_SPIN(xb_ld(&bar[XB_XGEN(b.x)]) == gen, bar);
;             __builtin_amdgcn_fence(__ATOMIC_ACQUIRE, "agent");
;             asm volatile("s_waitcnt vmcnt(0)" ::: "memory");
;         }
;     }
;     __syncthreads();
.LBB0_1285:
	s_waitcnt vmcnt(0) lgkmcnt(0)
	s_barrier
	v_readlane_b32 s2, v252, 0
	s_cmp_lg_u32 s2, 0
	s_cbranch_scc1 .Lfbf_done
	s_mov_b64 exec, 1
	v_mov_b32_e32 v0, 0x23ff8
	ds_read_b32 v2, v0
	s_waitcnt lgkmcnt(0)
	v_readfirstlane_b32 s3, v2
	s_cmp_eq_u32 s3, 1
	s_cbranch_scc0 .Lfbf_restore
	buffer_wbl2 sc1
	s_waitcnt vmcnt(0)
	s_add_u32 s8, s80, 0x101e0
	s_addc_u32 s9, s81, 0
	v_mov_b32_e32 v0, 0
	v_mov_b32_e32 v1, 1
	global_atomic_add v0, v1, s[8:9]
	s_mov_b32 s16, 0
.Lfbf_spin:
	s_sleep 1
	global_load_dword v2, v0, s[8:9] sc1
	s_add_i32 s16, s16, 1
	s_waitcnt vmcnt(0)
	v_readfirstlane_b32 s3, v2
	s_cmp_ge_u32 s3, s82
	s_cbranch_scc1 .Lfbf_rel
	s_cmp_lt_u32 s16, 0x8000
	s_cbranch_scc1 .Lfbf_spin
.Lfbf_rel:
	buffer_inv sc1
	s_waitcnt vmcnt(0)
.Lfbf_restore:
	s_mov_b64 exec, -1
.Lfbf_done:
	s_barrier
	v_readlane_b32 s0, v253, 40
	v_readlane_b32 s1, v253, 41
	s_andn2_b64 vcc, exec, s[0:1]
	s_cbranch_vccnz .LBB0_1294
	s_add_u32 s8, s80, 0x5c00000
	s_addc_u32 s9, s81, 0
	v_mov_b32_e32 v53, 0
	v_mov_b32_e32 v54, 0x358637bd
	s_mov_b32 s10, 0x800000
	s_branch .LBB0_1288
